# rwkv_prep: all row loads in flight, parameters hoisted, class branches replaced by constant exec masks
# baseline (speedup 1.0000x reference)
.LBB0_1029:
	s_mov_b64 s[4:5], s[0:1]
	s_mov_b32 s10, s2
	v_mov_b32_e32 v0, v154
	s_load_dwordx2 s[14:15], s[0:1], 0x138
	s_load_dwordx2 s[8:9], s[0:1], 0x88
	v_lshrrev_b32_e32 v40, 5, v154
	v_lshl_add_u32 v40, s2, 4, v40
	v_and_b32_e32 v41, 31, v154
	v_lshlrev_b32_e32 v41, 3, v41
	v_mul_u32_u24_e32 v42, 0x1e00, v40
	v_lshl_add_u32 v42, v41, 1, v42
	v_add_u32_e32 v43, 0x1000, v42
	v_lshlrev_b32_e32 v44, 9, v40
	v_lshl_add_u32 v44, v41, 1, v44
	v_or_b32_e32 v45, 0x600, v41
	v_lshlrev_b32_e32 v45, 2, v45
	v_and_b32_e32 v46, 0x7ff, v40
	v_cmp_ne_u32_e64 s[26:27], 0, v46
	s_mov_b32 s28, 0xff
	s_mov_b32 s29, 0xff
	s_mov_b32 s30, 0xffff0000
	s_mov_b32 s31, 0xffff0000
	s_waitcnt lgkmcnt(0)
	global_load_dwordx4 v[32:35], v45, s[8:9]
	global_load_dwordx4 v[36:39], v45, s[8:9] offset:16
	s_add_u32 s10, s14, 0x4300000
	s_addc_u32 s11, s15, 0
	global_load_dwordx4 v[0:3], v43, s[10:11] offset:3072
	global_load_dwordx4 v[4:7], v42, s[10:11] offset:-512
	s_add_u32 s10, s14, 0x6100000
	s_addc_u32 s11, s15, 0
	global_load_dwordx4 v[8:11], v43, s[10:11] offset:3072
	global_load_dwordx4 v[12:15], v42, s[10:11] offset:-512
	s_add_u32 s10, s14, 0x7f00000
	s_addc_u32 s11, s15, 0
	global_load_dwordx4 v[16:19], v43, s[10:11] offset:3072
	global_load_dwordx4 v[20:23], v42, s[10:11] offset:-512
	s_add_u32 s10, s14, 0x9d00000
	s_addc_u32 s11, s15, 0
	global_load_dwordx4 v[24:27], v43, s[10:11] offset:3072
	global_load_dwordx4 v[28:31], v42, s[10:11] offset:-512
	s_waitcnt vmcnt(6)
	v_cndmask_b32_e64 v4, 0, v4, s[26:27]
	v_cndmask_b32_e64 v5, 0, v5, s[26:27]
	v_cndmask_b32_e64 v6, 0, v6, s[26:27]
	v_cndmask_b32_e64 v7, 0, v7, s[26:27]
	v_lshlrev_b32_e32 v48, 16, v0
	v_and_b32_e32 v49, 0xffff0000, v0
	v_lshlrev_b32_e32 v56, 16, v4
	v_and_b32_e32 v57, 0xffff0000, v4
	v_lshlrev_b32_e32 v50, 16, v1
	v_and_b32_e32 v51, 0xffff0000, v1
	v_lshlrev_b32_e32 v58, 16, v5
	v_and_b32_e32 v59, 0xffff0000, v5
	v_lshlrev_b32_e32 v52, 16, v2
	v_and_b32_e32 v53, 0xffff0000, v2
	v_lshlrev_b32_e32 v60, 16, v6
	v_and_b32_e32 v61, 0xffff0000, v6
	v_lshlrev_b32_e32 v54, 16, v3
	v_and_b32_e32 v55, 0xffff0000, v3
	v_lshlrev_b32_e32 v62, 16, v7
	v_and_b32_e32 v63, 0xffff0000, v7
	v_sub_f32_e32 v56, v56, v48
	v_sub_f32_e32 v57, v57, v49
	v_sub_f32_e32 v58, v58, v50
	v_sub_f32_e32 v59, v59, v51
	v_sub_f32_e32 v60, v60, v52
	v_sub_f32_e32 v61, v61, v53
	v_sub_f32_e32 v62, v62, v54
	v_sub_f32_e32 v63, v63, v55
	v_fmac_f32_e32 v48, v32, v56
	v_fmac_f32_e32 v49, v33, v57
	v_fmac_f32_e32 v50, v34, v58
	v_fmac_f32_e32 v51, v35, v59
	v_fmac_f32_e32 v52, v36, v60
	v_fmac_f32_e32 v53, v37, v61
	v_fmac_f32_e32 v54, v38, v62
	v_fmac_f32_e32 v55, v39, v63
	s_mov_b64 exec, s[28:29]
	v_add_f32_e32 v56, v48, v48
	v_add_f32_e32 v57, v49, v49
	v_add_f32_e32 v58, v50, v50
	v_add_f32_e32 v59, v51, v51
	v_add_f32_e32 v60, v52, v52
	v_add_f32_e32 v61, v53, v53
	v_add_f32_e32 v62, v54, v54
	v_add_f32_e32 v63, v55, v55
	v_mul_f32_e32 v56, 0x3fb8aa3b, v56
	v_mul_f32_e32 v57, 0x3fb8aa3b, v57
	v_mul_f32_e32 v58, 0x3fb8aa3b, v58
	v_mul_f32_e32 v59, 0x3fb8aa3b, v59
	v_mul_f32_e32 v60, 0x3fb8aa3b, v60
	v_mul_f32_e32 v61, 0x3fb8aa3b, v61
	v_mul_f32_e32 v62, 0x3fb8aa3b, v62
	v_mul_f32_e32 v63, 0x3fb8aa3b, v63
	v_exp_f32_e32 v56, v56
	v_exp_f32_e32 v57, v57
	v_exp_f32_e32 v58, v58
	v_exp_f32_e32 v59, v59
	v_exp_f32_e32 v60, v60
	v_exp_f32_e32 v61, v61
	v_exp_f32_e32 v62, v62
	v_exp_f32_e32 v63, v63
	v_add_f32_e32 v56, 1.0, v56
	v_add_f32_e32 v57, 1.0, v57
	v_add_f32_e32 v58, 1.0, v58
	v_add_f32_e32 v59, 1.0, v59
	v_add_f32_e32 v60, 1.0, v60
	v_add_f32_e32 v61, 1.0, v61
	v_add_f32_e32 v62, 1.0, v62
	v_add_f32_e32 v63, 1.0, v63
	v_rcp_f32_e32 v56, v56
	v_rcp_f32_e32 v57, v57
	v_rcp_f32_e32 v58, v58
	v_rcp_f32_e32 v59, v59
	v_rcp_f32_e32 v60, v60
	v_rcp_f32_e32 v61, v61
	v_rcp_f32_e32 v62, v62
	v_rcp_f32_e32 v63, v63
	v_fma_f32 v48, v56, -2.0, 1.0
	v_fma_f32 v49, v57, -2.0, 1.0
	v_fma_f32 v50, v58, -2.0, 1.0
	v_fma_f32 v51, v59, -2.0, 1.0
	v_fma_f32 v52, v60, -2.0, 1.0
	v_fma_f32 v53, v61, -2.0, 1.0
	v_fma_f32 v54, v62, -2.0, 1.0
	v_fma_f32 v55, v63, -2.0, 1.0
	s_mov_b64 exec, s[30:31]
	v_mul_f32_e32 v56, 0xbfb8aa3b, v48
	v_mul_f32_e32 v57, 0xbfb8aa3b, v49
	v_mul_f32_e32 v58, 0xbfb8aa3b, v50
	v_mul_f32_e32 v59, 0xbfb8aa3b, v51
	v_mul_f32_e32 v60, 0xbfb8aa3b, v52
	v_mul_f32_e32 v61, 0xbfb8aa3b, v53
	v_mul_f32_e32 v62, 0xbfb8aa3b, v54
	v_mul_f32_e32 v63, 0xbfb8aa3b, v55
	v_exp_f32_e32 v56, v56
	v_exp_f32_e32 v57, v57
	v_exp_f32_e32 v58, v58
	v_exp_f32_e32 v59, v59
	v_exp_f32_e32 v60, v60
	v_exp_f32_e32 v61, v61
	v_exp_f32_e32 v62, v62
	v_exp_f32_e32 v63, v63
	v_add_f32_e32 v56, 1.0, v56
	v_add_f32_e32 v57, 1.0, v57
	v_add_f32_e32 v58, 1.0, v58
	v_add_f32_e32 v59, 1.0, v59
	v_add_f32_e32 v60, 1.0, v60
	v_add_f32_e32 v61, 1.0, v61
	v_add_f32_e32 v62, 1.0, v62
	v_add_f32_e32 v63, 1.0, v63
	v_rcp_f32_e32 v48, v56
	v_rcp_f32_e32 v49, v57
	v_rcp_f32_e32 v50, v58
	v_rcp_f32_e32 v51, v59
	v_rcp_f32_e32 v52, v60
	v_rcp_f32_e32 v53, v61
	v_rcp_f32_e32 v54, v62
	v_rcp_f32_e32 v55, v63
	s_mov_b64 exec, -1
	v_cvt_pk_bf16_f32 v64, v48, v49
	v_cvt_pk_bf16_f32 v65, v50, v51
	v_cvt_pk_bf16_f32 v66, v52, v53
	v_cvt_pk_bf16_f32 v67, v54, v55
	s_add_u32 s12, s14, 0xeb00000
	s_addc_u32 s13, s15, 0
	global_store_dwordx4 v44, v[64:67], s[12:13]
	s_waitcnt vmcnt(5)
	v_cndmask_b32_e64 v12, 0, v12, s[26:27]
	v_cndmask_b32_e64 v13, 0, v13, s[26:27]
	v_cndmask_b32_e64 v14, 0, v14, s[26:27]
	v_cndmask_b32_e64 v15, 0, v15, s[26:27]
	v_lshlrev_b32_e32 v48, 16, v8
	v_and_b32_e32 v49, 0xffff0000, v8
	v_lshlrev_b32_e32 v56, 16, v12
	v_and_b32_e32 v57, 0xffff0000, v12
	v_lshlrev_b32_e32 v50, 16, v9
	v_and_b32_e32 v51, 0xffff0000, v9
	v_lshlrev_b32_e32 v58, 16, v13
	v_and_b32_e32 v59, 0xffff0000, v13
	v_lshlrev_b32_e32 v52, 16, v10
	v_and_b32_e32 v53, 0xffff0000, v10
	v_lshlrev_b32_e32 v60, 16, v14
	v_and_b32_e32 v61, 0xffff0000, v14
	v_lshlrev_b32_e32 v54, 16, v11
	v_and_b32_e32 v55, 0xffff0000, v11
	v_lshlrev_b32_e32 v62, 16, v15
	v_and_b32_e32 v63, 0xffff0000, v15
	v_sub_f32_e32 v56, v56, v48
	v_sub_f32_e32 v57, v57, v49
	v_sub_f32_e32 v58, v58, v50
	v_sub_f32_e32 v59, v59, v51
	v_sub_f32_e32 v60, v60, v52
	v_sub_f32_e32 v61, v61, v53
	v_sub_f32_e32 v62, v62, v54
	v_sub_f32_e32 v63, v63, v55
	v_fmac_f32_e32 v48, v32, v56
	v_fmac_f32_e32 v49, v33, v57
	v_fmac_f32_e32 v50, v34, v58
	v_fmac_f32_e32 v51, v35, v59
	v_fmac_f32_e32 v52, v36, v60
	v_fmac_f32_e32 v53, v37, v61
	v_fmac_f32_e32 v54, v38, v62
	v_fmac_f32_e32 v55, v39, v63
	s_mov_b64 exec, s[28:29]
	v_add_f32_e32 v56, v48, v48
	v_add_f32_e32 v57, v49, v49
	v_add_f32_e32 v58, v50, v50
	v_add_f32_e32 v59, v51, v51
	v_add_f32_e32 v60, v52, v52
	v_add_f32_e32 v61, v53, v53
	v_add_f32_e32 v62, v54, v54
	v_add_f32_e32 v63, v55, v55
	v_mul_f32_e32 v56, 0x3fb8aa3b, v56
	v_mul_f32_e32 v57, 0x3fb8aa3b, v57
	v_mul_f32_e32 v58, 0x3fb8aa3b, v58
	v_mul_f32_e32 v59, 0x3fb8aa3b, v59
	v_mul_f32_e32 v60, 0x3fb8aa3b, v60
	v_mul_f32_e32 v61, 0x3fb8aa3b, v61
	v_mul_f32_e32 v62, 0x3fb8aa3b, v62
	v_mul_f32_e32 v63, 0x3fb8aa3b, v63
	v_exp_f32_e32 v56, v56
	v_exp_f32_e32 v57, v57
	v_exp_f32_e32 v58, v58
	v_exp_f32_e32 v59, v59
	v_exp_f32_e32 v60, v60
	v_exp_f32_e32 v61, v61
	v_exp_f32_e32 v62, v62
	v_exp_f32_e32 v63, v63
	v_add_f32_e32 v56, 1.0, v56
	v_add_f32_e32 v57, 1.0, v57
	v_add_f32_e32 v58, 1.0, v58
	v_add_f32_e32 v59, 1.0, v59
	v_add_f32_e32 v60, 1.0, v60
	v_add_f32_e32 v61, 1.0, v61
	v_add_f32_e32 v62, 1.0, v62
	v_add_f32_e32 v63, 1.0, v63
	v_rcp_f32_e32 v56, v56
	v_rcp_f32_e32 v57, v57
	v_rcp_f32_e32 v58, v58
	v_rcp_f32_e32 v59, v59
	v_rcp_f32_e32 v60, v60
	v_rcp_f32_e32 v61, v61
	v_rcp_f32_e32 v62, v62
	v_rcp_f32_e32 v63, v63
	v_fma_f32 v48, v56, -2.0, 1.0
	v_fma_f32 v49, v57, -2.0, 1.0
	v_fma_f32 v50, v58, -2.0, 1.0
	v_fma_f32 v51, v59, -2.0, 1.0
	v_fma_f32 v52, v60, -2.0, 1.0
	v_fma_f32 v53, v61, -2.0, 1.0
	v_fma_f32 v54, v62, -2.0, 1.0
	v_fma_f32 v55, v63, -2.0, 1.0
	s_mov_b64 exec, s[30:31]
	v_mul_f32_e32 v56, 0xbfb8aa3b, v48
	v_mul_f32_e32 v57, 0xbfb8aa3b, v49
	v_mul_f32_e32 v58, 0xbfb8aa3b, v50
	v_mul_f32_e32 v59, 0xbfb8aa3b, v51
	v_mul_f32_e32 v60, 0xbfb8aa3b, v52
	v_mul_f32_e32 v61, 0xbfb8aa3b, v53
	v_mul_f32_e32 v62, 0xbfb8aa3b, v54
	v_mul_f32_e32 v63, 0xbfb8aa3b, v55
	v_exp_f32_e32 v56, v56
	v_exp_f32_e32 v57, v57
	v_exp_f32_e32 v58, v58
	v_exp_f32_e32 v59, v59
	v_exp_f32_e32 v60, v60
	v_exp_f32_e32 v61, v61
	v_exp_f32_e32 v62, v62
	v_exp_f32_e32 v63, v63
	v_add_f32_e32 v56, 1.0, v56
	v_add_f32_e32 v57, 1.0, v57
	v_add_f32_e32 v58, 1.0, v58
	v_add_f32_e32 v59, 1.0, v59
	v_add_f32_e32 v60, 1.0, v60
	v_add_f32_e32 v61, 1.0, v61
	v_add_f32_e32 v62, 1.0, v62
	v_add_f32_e32 v63, 1.0, v63
	v_rcp_f32_e32 v48, v56
	v_rcp_f32_e32 v49, v57
	v_rcp_f32_e32 v50, v58
	v_rcp_f32_e32 v51, v59
	v_rcp_f32_e32 v52, v60
	v_rcp_f32_e32 v53, v61
	v_rcp_f32_e32 v54, v62
	v_rcp_f32_e32 v55, v63
	s_mov_b64 exec, -1
	v_cvt_pk_bf16_f32 v68, v48, v49
	v_cvt_pk_bf16_f32 v69, v50, v51
	v_cvt_pk_bf16_f32 v70, v52, v53
	v_cvt_pk_bf16_f32 v71, v54, v55
	s_add_u32 s12, s14, 0xed00000
	s_addc_u32 s13, s15, 0
	global_store_dwordx4 v44, v[68:71], s[12:13]
	s_waitcnt vmcnt(4)
	v_cndmask_b32_e64 v20, 0, v20, s[26:27]
	v_cndmask_b32_e64 v21, 0, v21, s[26:27]
	v_cndmask_b32_e64 v22, 0, v22, s[26:27]
	v_cndmask_b32_e64 v23, 0, v23, s[26:27]
	v_lshlrev_b32_e32 v48, 16, v16
	v_and_b32_e32 v49, 0xffff0000, v16
	v_lshlrev_b32_e32 v56, 16, v20
	v_and_b32_e32 v57, 0xffff0000, v20
	v_lshlrev_b32_e32 v50, 16, v17
	v_and_b32_e32 v51, 0xffff0000, v17
	v_lshlrev_b32_e32 v58, 16, v21
	v_and_b32_e32 v59, 0xffff0000, v21
	v_lshlrev_b32_e32 v52, 16, v18
	v_and_b32_e32 v53, 0xffff0000, v18
	v_lshlrev_b32_e32 v60, 16, v22
	v_and_b32_e32 v61, 0xffff0000, v22
	v_lshlrev_b32_e32 v54, 16, v19
	v_and_b32_e32 v55, 0xffff0000, v19
	v_lshlrev_b32_e32 v62, 16, v23
	v_and_b32_e32 v63, 0xffff0000, v23
	v_sub_f32_e32 v56, v56, v48
	v_sub_f32_e32 v57, v57, v49
	v_sub_f32_e32 v58, v58, v50
	v_sub_f32_e32 v59, v59, v51
	v_sub_f32_e32 v60, v60, v52
	v_sub_f32_e32 v61, v61, v53
	v_sub_f32_e32 v62, v62, v54
	v_sub_f32_e32 v63, v63, v55
	v_fmac_f32_e32 v48, v32, v56
	v_fmac_f32_e32 v49, v33, v57
	v_fmac_f32_e32 v50, v34, v58
	v_fmac_f32_e32 v51, v35, v59
	v_fmac_f32_e32 v52, v36, v60
	v_fmac_f32_e32 v53, v37, v61
	v_fmac_f32_e32 v54, v38, v62
	v_fmac_f32_e32 v55, v39, v63
	s_mov_b64 exec, s[28:29]
	v_add_f32_e32 v56, v48, v48
	v_add_f32_e32 v57, v49, v49
	v_add_f32_e32 v58, v50, v50
	v_add_f32_e32 v59, v51, v51
	v_add_f32_e32 v60, v52, v52
	v_add_f32_e32 v61, v53, v53
	v_add_f32_e32 v62, v54, v54
	v_add_f32_e32 v63, v55, v55
	v_mul_f32_e32 v56, 0x3fb8aa3b, v56
	v_mul_f32_e32 v57, 0x3fb8aa3b, v57
	v_mul_f32_e32 v58, 0x3fb8aa3b, v58
	v_mul_f32_e32 v59, 0x3fb8aa3b, v59
	v_mul_f32_e32 v60, 0x3fb8aa3b, v60
	v_mul_f32_e32 v61, 0x3fb8aa3b, v61
	v_mul_f32_e32 v62, 0x3fb8aa3b, v62
	v_mul_f32_e32 v63, 0x3fb8aa3b, v63
	v_exp_f32_e32 v56, v56
	v_exp_f32_e32 v57, v57
	v_exp_f32_e32 v58, v58
	v_exp_f32_e32 v59, v59
	v_exp_f32_e32 v60, v60
	v_exp_f32_e32 v61, v61
	v_exp_f32_e32 v62, v62
	v_exp_f32_e32 v63, v63
	v_add_f32_e32 v56, 1.0, v56
	v_add_f32_e32 v57, 1.0, v57
	v_add_f32_e32 v58, 1.0, v58
	v_add_f32_e32 v59, 1.0, v59
	v_add_f32_e32 v60, 1.0, v60
	v_add_f32_e32 v61, 1.0, v61
	v_add_f32_e32 v62, 1.0, v62
	v_add_f32_e32 v63, 1.0, v63
	v_rcp_f32_e32 v56, v56
	v_rcp_f32_e32 v57, v57
	v_rcp_f32_e32 v58, v58
	v_rcp_f32_e32 v59, v59
	v_rcp_f32_e32 v60, v60
	v_rcp_f32_e32 v61, v61
	v_rcp_f32_e32 v62, v62
	v_rcp_f32_e32 v63, v63
	v_fma_f32 v48, v56, -2.0, 1.0
	v_fma_f32 v49, v57, -2.0, 1.0
	v_fma_f32 v50, v58, -2.0, 1.0
	v_fma_f32 v51, v59, -2.0, 1.0
	v_fma_f32 v52, v60, -2.0, 1.0
	v_fma_f32 v53, v61, -2.0, 1.0
	v_fma_f32 v54, v62, -2.0, 1.0
	v_fma_f32 v55, v63, -2.0, 1.0
	s_mov_b64 exec, s[30:31]
	v_mul_f32_e32 v56, 0xbfb8aa3b, v48
	v_mul_f32_e32 v57, 0xbfb8aa3b, v49
	v_mul_f32_e32 v58, 0xbfb8aa3b, v50
	v_mul_f32_e32 v59, 0xbfb8aa3b, v51
	v_mul_f32_e32 v60, 0xbfb8aa3b, v52
	v_mul_f32_e32 v61, 0xbfb8aa3b, v53
	v_mul_f32_e32 v62, 0xbfb8aa3b, v54
	v_mul_f32_e32 v63, 0xbfb8aa3b, v55
	v_exp_f32_e32 v56, v56
	v_exp_f32_e32 v57, v57
	v_exp_f32_e32 v58, v58
	v_exp_f32_e32 v59, v59
	v_exp_f32_e32 v60, v60
	v_exp_f32_e32 v61, v61
	v_exp_f32_e32 v62, v62
	v_exp_f32_e32 v63, v63
	v_add_f32_e32 v56, 1.0, v56
	v_add_f32_e32 v57, 1.0, v57
	v_add_f32_e32 v58, 1.0, v58
	v_add_f32_e32 v59, 1.0, v59
	v_add_f32_e32 v60, 1.0, v60
	v_add_f32_e32 v61, 1.0, v61
	v_add_f32_e32 v62, 1.0, v62
	v_add_f32_e32 v63, 1.0, v63
	v_rcp_f32_e32 v48, v56
	v_rcp_f32_e32 v49, v57
	v_rcp_f32_e32 v50, v58
	v_rcp_f32_e32 v51, v59
	v_rcp_f32_e32 v52, v60
	v_rcp_f32_e32 v53, v61
	v_rcp_f32_e32 v54, v62
	v_rcp_f32_e32 v55, v63
	s_mov_b64 exec, -1
	v_cvt_pk_bf16_f32 v72, v48, v49
	v_cvt_pk_bf16_f32 v73, v50, v51
	v_cvt_pk_bf16_f32 v74, v52, v53
	v_cvt_pk_bf16_f32 v75, v54, v55
	s_add_u32 s12, s14, 0xef00000
	s_addc_u32 s13, s15, 0
	global_store_dwordx4 v44, v[72:75], s[12:13]
	s_waitcnt vmcnt(3)
	v_cndmask_b32_e64 v28, 0, v28, s[26:27]
	v_cndmask_b32_e64 v29, 0, v29, s[26:27]
	v_cndmask_b32_e64 v30, 0, v30, s[26:27]
	v_cndmask_b32_e64 v31, 0, v31, s[26:27]
	v_lshlrev_b32_e32 v48, 16, v24
	v_and_b32_e32 v49, 0xffff0000, v24
	v_lshlrev_b32_e32 v56, 16, v28
	v_and_b32_e32 v57, 0xffff0000, v28
	v_lshlrev_b32_e32 v50, 16, v25
	v_and_b32_e32 v51, 0xffff0000, v25
	v_lshlrev_b32_e32 v58, 16, v29
	v_and_b32_e32 v59, 0xffff0000, v29
	v_lshlrev_b32_e32 v52, 16, v26
	v_and_b32_e32 v53, 0xffff0000, v26
	v_lshlrev_b32_e32 v60, 16, v30
	v_and_b32_e32 v61, 0xffff0000, v30
	v_lshlrev_b32_e32 v54, 16, v27
	v_and_b32_e32 v55, 0xffff0000, v27
	v_lshlrev_b32_e32 v62, 16, v31
	v_and_b32_e32 v63, 0xffff0000, v31
	v_sub_f32_e32 v56, v56, v48
	v_sub_f32_e32 v57, v57, v49
	v_sub_f32_e32 v58, v58, v50
	v_sub_f32_e32 v59, v59, v51
	v_sub_f32_e32 v60, v60, v52
	v_sub_f32_e32 v61, v61, v53
	v_sub_f32_e32 v62, v62, v54
	v_sub_f32_e32 v63, v63, v55
	v_fmac_f32_e32 v48, v32, v56
	v_fmac_f32_e32 v49, v33, v57
	v_fmac_f32_e32 v50, v34, v58
	v_fmac_f32_e32 v51, v35, v59
	v_fmac_f32_e32 v52, v36, v60
	v_fmac_f32_e32 v53, v37, v61
	v_fmac_f32_e32 v54, v38, v62
	v_fmac_f32_e32 v55, v39, v63
	s_mov_b64 exec, s[28:29]
	v_add_f32_e32 v56, v48, v48
	v_add_f32_e32 v57, v49, v49
	v_add_f32_e32 v58, v50, v50
	v_add_f32_e32 v59, v51, v51
	v_add_f32_e32 v60, v52, v52
	v_add_f32_e32 v61, v53, v53
	v_add_f32_e32 v62, v54, v54
	v_add_f32_e32 v63, v55, v55
	v_mul_f32_e32 v56, 0x3fb8aa3b, v56
	v_mul_f32_e32 v57, 0x3fb8aa3b, v57
	v_mul_f32_e32 v58, 0x3fb8aa3b, v58
	v_mul_f32_e32 v59, 0x3fb8aa3b, v59
	v_mul_f32_e32 v60, 0x3fb8aa3b, v60
	v_mul_f32_e32 v61, 0x3fb8aa3b, v61
	v_mul_f32_e32 v62, 0x3fb8aa3b, v62
	v_mul_f32_e32 v63, 0x3fb8aa3b, v63
	v_exp_f32_e32 v56, v56
	v_exp_f32_e32 v57, v57
	v_exp_f32_e32 v58, v58
	v_exp_f32_e32 v59, v59
	v_exp_f32_e32 v60, v60
	v_exp_f32_e32 v61, v61
	v_exp_f32_e32 v62, v62
	v_exp_f32_e32 v63, v63
	v_add_f32_e32 v56, 1.0, v56
	v_add_f32_e32 v57, 1.0, v57
	v_add_f32_e32 v58, 1.0, v58
	v_add_f32_e32 v59, 1.0, v59
	v_add_f32_e32 v60, 1.0, v60
	v_add_f32_e32 v61, 1.0, v61
	v_add_f32_e32 v62, 1.0, v62
	v_add_f32_e32 v63, 1.0, v63
	v_rcp_f32_e32 v56, v56
	v_rcp_f32_e32 v57, v57
	v_rcp_f32_e32 v58, v58
	v_rcp_f32_e32 v59, v59
	v_rcp_f32_e32 v60, v60
	v_rcp_f32_e32 v61, v61
	v_rcp_f32_e32 v62, v62
	v_rcp_f32_e32 v63, v63
	v_fma_f32 v48, v56, -2.0, 1.0
	v_fma_f32 v49, v57, -2.0, 1.0
	v_fma_f32 v50, v58, -2.0, 1.0
	v_fma_f32 v51, v59, -2.0, 1.0
	v_fma_f32 v52, v60, -2.0, 1.0
	v_fma_f32 v53, v61, -2.0, 1.0
	v_fma_f32 v54, v62, -2.0, 1.0
	v_fma_f32 v55, v63, -2.0, 1.0
	s_mov_b64 exec, s[30:31]
	v_mul_f32_e32 v56, 0xbfb8aa3b, v48
	v_mul_f32_e32 v57, 0xbfb8aa3b, v49
	v_mul_f32_e32 v58, 0xbfb8aa3b, v50
	v_mul_f32_e32 v59, 0xbfb8aa3b, v51
	v_mul_f32_e32 v60, 0xbfb8aa3b, v52
	v_mul_f32_e32 v61, 0xbfb8aa3b, v53
	v_mul_f32_e32 v62, 0xbfb8aa3b, v54
	v_mul_f32_e32 v63, 0xbfb8aa3b, v55
	v_exp_f32_e32 v56, v56
	v_exp_f32_e32 v57, v57
	v_exp_f32_e32 v58, v58
	v_exp_f32_e32 v59, v59
	v_exp_f32_e32 v60, v60
	v_exp_f32_e32 v61, v61
	v_exp_f32_e32 v62, v62
	v_exp_f32_e32 v63, v63
	v_add_f32_e32 v56, 1.0, v56
	v_add_f32_e32 v57, 1.0, v57
	v_add_f32_e32 v58, 1.0, v58
	v_add_f32_e32 v59, 1.0, v59
	v_add_f32_e32 v60, 1.0, v60
	v_add_f32_e32 v61, 1.0, v61
	v_add_f32_e32 v62, 1.0, v62
	v_add_f32_e32 v63, 1.0, v63
	v_rcp_f32_e32 v48, v56
	v_rcp_f32_e32 v49, v57
	v_rcp_f32_e32 v50, v58
	v_rcp_f32_e32 v51, v59
	v_rcp_f32_e32 v52, v60
	v_rcp_f32_e32 v53, v61
	v_rcp_f32_e32 v54, v62
	v_rcp_f32_e32 v55, v63
	s_mov_b64 exec, -1
	v_cvt_pk_bf16_f32 v76, v48, v49
	v_cvt_pk_bf16_f32 v77, v50, v51
	v_cvt_pk_bf16_f32 v78, v52, v53
	v_cvt_pk_bf16_f32 v79, v54, v55
	s_add_u32 s12, s14, 0xf100000
	s_addc_u32 s13, s15, 0
	global_store_dwordx4 v44, v[76:79], s[12:13]
	s_mov_b64 s[6:7], 0
